# GEMM0/GEMM1 K loops: LDS writes and global loads spread evenly over the whole MFMA sequence (slot table) instead of clustered at the end
# speedup vs baseline: 1.0157x; 1.0080x over previous
.Lgq_c:
	ds_read_b128 v[114:117], v188 offset:16384
	ds_read_b128 v[118:121], v188 offset:16896
	ds_read_b128 v[156:159], v188 offset:20480
	ds_read_b128 v[160:163], v188 offset:20992
	ds_read_b128 v[122:125], v112
	ds_read_b128 v[126:129], v112 offset:2048
	s_waitcnt lgkmcnt(1)
	v_mfma_f32_16x16x32_bf16 v[66:69], v[114:117], v[122:125], v[66:69]
	s_waitcnt vmcnt(7)
	ds_write_b128 v110, v[224:227] offset:32768
	v_mfma_f32_16x16x32_bf16 v[58:61], v[118:121], v[122:125], v[58:61]
	global_load_dwordx4 v[62:65], v216, s[0:1] offset:256
	v_mfma_f32_16x16x32_bf16 v[54:57], v[156:159], v[122:125], v[54:57]
	v_mfma_f32_16x16x32_bf16 v[50:53], v[160:163], v[122:125], v[50:53]
	s_waitcnt vmcnt(7)
	ds_write_b128 v110, v[228:231] offset:36864
	s_waitcnt lgkmcnt(2)
	v_mfma_f32_16x16x32_bf16 v[46:49], v[114:117], v[126:129], v[46:49]
	ds_read_b128 v[180:183], v112 offset:4096
	ds_read_b128 v[184:187], v112 offset:6144
	v_mfma_f32_16x16x32_bf16 v[42:45], v[118:121], v[126:129], v[42:45]
	global_load_dwordx4 v[70:73], v217, s[0:1] offset:256
	v_mfma_f32_16x16x32_bf16 v[38:41], v[156:159], v[126:129], v[38:41]
	s_waitcnt vmcnt(7)
	ds_write_b128 v110, v[232:235] offset:40960
	v_mfma_f32_16x16x32_bf16 v[34:37], v[160:163], v[126:129], v[34:37]
	s_waitcnt lgkmcnt(2)
	v_mfma_f32_16x16x32_bf16 v[30:33], v[114:117], v[180:183], v[30:33]
	ds_read_b128 v[164:167], v189 offset:16384
	ds_read_b128 v[168:171], v189 offset:16896
	v_mfma_f32_16x16x32_bf16 v[26:29], v[118:121], v[180:183], v[26:29]
	s_waitcnt vmcnt(6)
	ds_write_b128 v110, v[236:239] offset:45056
	v_mfma_f32_16x16x32_bf16 v[22:25], v[156:159], v[180:183], v[22:25]
	ds_read_b128 v[172:175], v189 offset:20480
	ds_read_b128 v[176:179], v189 offset:20992
	v_mfma_f32_16x16x32_bf16 v[18:21], v[160:163], v[180:183], v[18:21]
	global_load_dwordx4 v[74:77], v218, s[0:1] offset:256
	s_waitcnt lgkmcnt(6)
	v_mfma_f32_16x16x32_bf16 v[14:17], v[114:117], v[184:187], v[14:17]
	ds_read_b128 v[122:125], v113
	ds_read_b128 v[126:129], v113 offset:2048
	v_mfma_f32_16x16x32_bf16 v[10:13], v[118:121], v[184:187], v[10:13]
	s_waitcnt vmcnt(6)
	ds_write_b128 v190, v[240:243] offset:49168
	v_mfma_f32_16x16x32_bf16 v[6:9], v[156:159], v[184:187], v[6:9]
	global_load_dwordx4 v[78:81], v219, s[0:1] offset:256
	v_mfma_f32_16x16x32_bf16 v[2:5], v[160:163], v[184:187], v[2:5]
	s_waitcnt lgkmcnt(2)
	v_mfma_f32_16x16x32_bf16 v[66:69], v[164:167], v[122:125], v[66:69]
	s_waitcnt vmcnt(6)
	ds_write_b128 v190, v[244:247] offset:53264
	v_mfma_f32_16x16x32_bf16 v[58:61], v[168:171], v[122:125], v[58:61]
	global_load_dwordx4 v[82:85], v216, s[6:7] offset:256
	v_mfma_f32_16x16x32_bf16 v[54:57], v[172:175], v[122:125], v[54:57]
	v_mfma_f32_16x16x32_bf16 v[50:53], v[176:179], v[122:125], v[50:53]
	s_waitcnt vmcnt(6)
	ds_write_b128 v190, v[248:251] offset:57360
	s_waitcnt lgkmcnt(3)
	v_mfma_f32_16x16x32_bf16 v[46:49], v[164:167], v[126:129], v[46:49]
	ds_read_b128 v[180:183], v113 offset:4096
	ds_read_b128 v[184:187], v113 offset:6144
	v_mfma_f32_16x16x32_bf16 v[42:45], v[168:171], v[126:129], v[42:45]
	global_load_dwordx4 v[86:89], v217, s[6:7] offset:256
	v_mfma_f32_16x16x32_bf16 v[38:41], v[172:175], v[126:129], v[38:41]
	s_waitcnt vmcnt(6)
	ds_write_b128 v190, v[252:255] offset:61456
	v_mfma_f32_16x16x32_bf16 v[34:37], v[176:179], v[126:129], v[34:37]
	s_waitcnt lgkmcnt(2)
	v_mfma_f32_16x16x32_bf16 v[30:33], v[164:167], v[180:183], v[30:33]
	global_load_dwordx4 v[90:93], v218, s[6:7] offset:256
	v_mfma_f32_16x16x32_bf16 v[26:29], v[168:171], v[180:183], v[26:29]
	v_mfma_f32_16x16x32_bf16 v[22:25], v[172:175], v[180:183], v[22:25]
	v_mfma_f32_16x16x32_bf16 v[18:21], v[176:179], v[180:183], v[18:21]
	global_load_dwordx4 v[94:97], v219, s[6:7] offset:256
	s_waitcnt lgkmcnt(1)
	v_mfma_f32_16x16x32_bf16 v[14:17], v[164:167], v[184:187], v[14:17]
	v_mfma_f32_16x16x32_bf16 v[10:13], v[168:171], v[184:187], v[10:13]
	v_mfma_f32_16x16x32_bf16 v[6:9], v[172:175], v[184:187], v[6:9]
	v_mfma_f32_16x16x32_bf16 v[2:5], v[176:179], v[184:187], v[2:5]
	s_waitcnt lgkmcnt(0)
	s_barrier
	s_add_u32 s0, s0, 0x80
	s_addc_u32 s1, s1, 0
	s_add_u32 s6, s6, 0x80
	s_addc_u32 s7, s7, 0
	ds_read_b128 v[114:117], v188 offset:49168
	ds_read_b128 v[118:121], v188 offset:49680
	ds_read_b128 v[156:159], v188 offset:53264
	ds_read_b128 v[160:163], v188 offset:53776
	ds_read_b128 v[122:125], v112 offset:32768
	ds_read_b128 v[126:129], v112 offset:34816
	s_waitcnt lgkmcnt(1)
	v_mfma_f32_16x16x32_bf16 v[66:69], v[114:117], v[122:125], v[66:69]
	s_waitcnt vmcnt(7)
	ds_write_b128 v110, v[62:65]
	v_mfma_f32_16x16x32_bf16 v[58:61], v[118:121], v[122:125], v[58:61]
	global_load_dwordx4 v[224:227], v216, s[0:1] offset:256
	v_mfma_f32_16x16x32_bf16 v[54:57], v[156:159], v[122:125], v[54:57]
	v_mfma_f32_16x16x32_bf16 v[50:53], v[160:163], v[122:125], v[50:53]
	s_waitcnt vmcnt(7)
	ds_write_b128 v110, v[70:73] offset:4096
	s_waitcnt lgkmcnt(2)
	v_mfma_f32_16x16x32_bf16 v[46:49], v[114:117], v[126:129], v[46:49]
	ds_read_b128 v[180:183], v112 offset:36864
	ds_read_b128 v[184:187], v112 offset:38912
	v_mfma_f32_16x16x32_bf16 v[42:45], v[118:121], v[126:129], v[42:45]
	global_load_dwordx4 v[228:231], v217, s[0:1] offset:256
	v_mfma_f32_16x16x32_bf16 v[38:41], v[156:159], v[126:129], v[38:41]
	s_waitcnt vmcnt(7)
	ds_write_b128 v110, v[74:77] offset:8192
	v_mfma_f32_16x16x32_bf16 v[34:37], v[160:163], v[126:129], v[34:37]
	s_waitcnt lgkmcnt(2)
	v_mfma_f32_16x16x32_bf16 v[30:33], v[114:117], v[180:183], v[30:33]
	ds_read_b128 v[164:167], v189 offset:49168
	ds_read_b128 v[168:171], v189 offset:49680
	v_mfma_f32_16x16x32_bf16 v[26:29], v[118:121], v[180:183], v[26:29]
	s_waitcnt vmcnt(6)
	ds_write_b128 v110, v[78:81] offset:12288
	v_mfma_f32_16x16x32_bf16 v[22:25], v[156:159], v[180:183], v[22:25]
	ds_read_b128 v[172:175], v189 offset:53264
	ds_read_b128 v[176:179], v189 offset:53776
	v_mfma_f32_16x16x32_bf16 v[18:21], v[160:163], v[180:183], v[18:21]
	global_load_dwordx4 v[232:235], v218, s[0:1] offset:256
	s_waitcnt lgkmcnt(6)
	v_mfma_f32_16x16x32_bf16 v[14:17], v[114:117], v[184:187], v[14:17]
	ds_read_b128 v[122:125], v113 offset:32768
	ds_read_b128 v[126:129], v113 offset:34816
	v_mfma_f32_16x16x32_bf16 v[10:13], v[118:121], v[184:187], v[10:13]
	s_waitcnt vmcnt(6)
	ds_write_b128 v190, v[82:85] offset:16384
	v_mfma_f32_16x16x32_bf16 v[6:9], v[156:159], v[184:187], v[6:9]
	global_load_dwordx4 v[236:239], v219, s[0:1] offset:256
	v_mfma_f32_16x16x32_bf16 v[2:5], v[160:163], v[184:187], v[2:5]
	s_waitcnt lgkmcnt(2)
	v_mfma_f32_16x16x32_bf16 v[66:69], v[164:167], v[122:125], v[66:69]
	s_waitcnt vmcnt(6)
	ds_write_b128 v190, v[86:89] offset:20480
	v_mfma_f32_16x16x32_bf16 v[58:61], v[168:171], v[122:125], v[58:61]
	global_load_dwordx4 v[240:243], v216, s[6:7] offset:256
	v_mfma_f32_16x16x32_bf16 v[54:57], v[172:175], v[122:125], v[54:57]
	v_mfma_f32_16x16x32_bf16 v[50:53], v[176:179], v[122:125], v[50:53]
	s_waitcnt vmcnt(6)
	ds_write_b128 v190, v[90:93] offset:24576
	s_waitcnt lgkmcnt(3)
	v_mfma_f32_16x16x32_bf16 v[46:49], v[164:167], v[126:129], v[46:49]
	ds_read_b128 v[180:183], v113 offset:36864
	ds_read_b128 v[184:187], v113 offset:38912
	v_mfma_f32_16x16x32_bf16 v[42:45], v[168:171], v[126:129], v[42:45]
	global_load_dwordx4 v[244:247], v217, s[6:7] offset:256
	v_mfma_f32_16x16x32_bf16 v[38:41], v[172:175], v[126:129], v[38:41]
	s_waitcnt vmcnt(6)
	ds_write_b128 v190, v[94:97] offset:28672
	v_mfma_f32_16x16x32_bf16 v[34:37], v[176:179], v[126:129], v[34:37]
	s_waitcnt lgkmcnt(2)
	v_mfma_f32_16x16x32_bf16 v[30:33], v[164:167], v[180:183], v[30:33]
	global_load_dwordx4 v[248:251], v218, s[6:7] offset:256
	v_mfma_f32_16x16x32_bf16 v[26:29], v[168:171], v[180:183], v[26:29]
	v_mfma_f32_16x16x32_bf16 v[22:25], v[172:175], v[180:183], v[22:25]
	v_mfma_f32_16x16x32_bf16 v[18:21], v[176:179], v[180:183], v[18:21]
	global_load_dwordx4 v[252:255], v219, s[6:7] offset:256
	s_waitcnt lgkmcnt(1)
	v_mfma_f32_16x16x32_bf16 v[14:17], v[164:167], v[184:187], v[14:17]
	v_mfma_f32_16x16x32_bf16 v[10:13], v[168:171], v[184:187], v[10:13]
	v_mfma_f32_16x16x32_bf16 v[6:9], v[172:175], v[184:187], v[6:9]
	v_mfma_f32_16x16x32_bf16 v[2:5], v[176:179], v[184:187], v[2:5]
	s_waitcnt lgkmcnt(0)
	s_barrier
	s_add_u32 s0, s0, 0x80
	s_addc_u32 s1, s1, 0
	s_add_u32 s6, s6, 0x80
	s_addc_u32 s7, s7, 0
	s_sub_i32 vcc_lo, vcc_lo, 1
	s_cmp_lg_u32 vcc_lo, 0
	s_cbranch_scc1 .Lgq_c
	ds_read_b128 v[114:117], v188 offset:16384
	ds_read_b128 v[118:121], v188 offset:16896
	ds_read_b128 v[156:159], v188 offset:20480
	ds_read_b128 v[160:163], v188 offset:20992
	ds_read_b128 v[122:125], v112
	ds_read_b128 v[126:129], v112 offset:2048
	s_waitcnt lgkmcnt(1)
	v_mfma_f32_16x16x32_bf16 v[66:69], v[114:117], v[122:125], v[66:69]
	s_waitcnt vmcnt(7)
	ds_write_b128 v110, v[224:227] offset:32768
	v_mfma_f32_16x16x32_bf16 v[58:61], v[118:121], v[122:125], v[58:61]
	v_mfma_f32_16x16x32_bf16 v[54:57], v[156:159], v[122:125], v[54:57]
	v_mfma_f32_16x16x32_bf16 v[50:53], v[160:163], v[122:125], v[50:53]
	s_waitcnt vmcnt(6)
	ds_write_b128 v110, v[228:231] offset:36864
	s_waitcnt lgkmcnt(2)
	v_mfma_f32_16x16x32_bf16 v[46:49], v[114:117], v[126:129], v[46:49]
	ds_read_b128 v[180:183], v112 offset:4096
	ds_read_b128 v[184:187], v112 offset:6144
	v_mfma_f32_16x16x32_bf16 v[42:45], v[118:121], v[126:129], v[42:45]
	v_mfma_f32_16x16x32_bf16 v[38:41], v[156:159], v[126:129], v[38:41]
	s_waitcnt vmcnt(5)
	ds_write_b128 v110, v[232:235] offset:40960
	v_mfma_f32_16x16x32_bf16 v[34:37], v[160:163], v[126:129], v[34:37]
	s_waitcnt lgkmcnt(2)
	v_mfma_f32_16x16x32_bf16 v[30:33], v[114:117], v[180:183], v[30:33]
	ds_read_b128 v[164:167], v189 offset:16384
	ds_read_b128 v[168:171], v189 offset:16896
	v_mfma_f32_16x16x32_bf16 v[26:29], v[118:121], v[180:183], v[26:29]
	s_waitcnt vmcnt(4)
	ds_write_b128 v110, v[236:239] offset:45056
	v_mfma_f32_16x16x32_bf16 v[22:25], v[156:159], v[180:183], v[22:25]
	ds_read_b128 v[172:175], v189 offset:20480
	ds_read_b128 v[176:179], v189 offset:20992
	v_mfma_f32_16x16x32_bf16 v[18:21], v[160:163], v[180:183], v[18:21]
	s_waitcnt lgkmcnt(6)
	v_mfma_f32_16x16x32_bf16 v[14:17], v[114:117], v[184:187], v[14:17]
	ds_read_b128 v[122:125], v113
	ds_read_b128 v[126:129], v113 offset:2048
	v_mfma_f32_16x16x32_bf16 v[10:13], v[118:121], v[184:187], v[10:13]
	s_waitcnt vmcnt(3)
	ds_write_b128 v190, v[240:243] offset:49168
	v_mfma_f32_16x16x32_bf16 v[6:9], v[156:159], v[184:187], v[6:9]
	v_mfma_f32_16x16x32_bf16 v[2:5], v[160:163], v[184:187], v[2:5]
	s_waitcnt lgkmcnt(2)
	v_mfma_f32_16x16x32_bf16 v[66:69], v[164:167], v[122:125], v[66:69]
	s_waitcnt vmcnt(2)
	ds_write_b128 v190, v[244:247] offset:53264
	v_mfma_f32_16x16x32_bf16 v[58:61], v[168:171], v[122:125], v[58:61]
	v_mfma_f32_16x16x32_bf16 v[54:57], v[172:175], v[122:125], v[54:57]
	v_mfma_f32_16x16x32_bf16 v[50:53], v[176:179], v[122:125], v[50:53]
	s_waitcnt vmcnt(1)
	ds_write_b128 v190, v[248:251] offset:57360
	s_waitcnt lgkmcnt(3)
	v_mfma_f32_16x16x32_bf16 v[46:49], v[164:167], v[126:129], v[46:49]
	ds_read_b128 v[180:183], v113 offset:4096
	ds_read_b128 v[184:187], v113 offset:6144
	v_mfma_f32_16x16x32_bf16 v[42:45], v[168:171], v[126:129], v[42:45]
	v_mfma_f32_16x16x32_bf16 v[38:41], v[172:175], v[126:129], v[38:41]
	s_waitcnt vmcnt(0)
	ds_write_b128 v190, v[252:255] offset:61456
	v_mfma_f32_16x16x32_bf16 v[34:37], v[176:179], v[126:129], v[34:37]
	s_waitcnt lgkmcnt(2)
	v_mfma_f32_16x16x32_bf16 v[30:33], v[164:167], v[180:183], v[30:33]
	v_mfma_f32_16x16x32_bf16 v[26:29], v[168:171], v[180:183], v[26:29]
	v_mfma_f32_16x16x32_bf16 v[22:25], v[172:175], v[180:183], v[22:25]
	v_mfma_f32_16x16x32_bf16 v[18:21], v[176:179], v[180:183], v[18:21]
	s_waitcnt lgkmcnt(1)
	v_mfma_f32_16x16x32_bf16 v[14:17], v[164:167], v[184:187], v[14:17]
	v_mfma_f32_16x16x32_bf16 v[10:13], v[168:171], v[184:187], v[10:13]
	v_mfma_f32_16x16x32_bf16 v[6:9], v[172:175], v[184:187], v[6:9]
	v_mfma_f32_16x16x32_bf16 v[2:5], v[176:179], v[184:187], v[2:5]
	s_waitcnt lgkmcnt(0)
	s_barrier
	ds_read_b128 v[114:117], v188 offset:49168
	ds_read_b128 v[118:121], v188 offset:49680
	ds_read_b128 v[156:159], v188 offset:53264
	ds_read_b128 v[160:163], v188 offset:53776
	ds_read_b128 v[122:125], v112 offset:32768
	ds_read_b128 v[126:129], v112 offset:34816
	s_waitcnt lgkmcnt(1)
	v_mfma_f32_16x16x32_bf16 v[66:69], v[114:117], v[122:125], v[66:69]
	v_mfma_f32_16x16x32_bf16 v[58:61], v[118:121], v[122:125], v[58:61]
	v_mfma_f32_16x16x32_bf16 v[54:57], v[156:159], v[122:125], v[54:57]
	v_mfma_f32_16x16x32_bf16 v[50:53], v[160:163], v[122:125], v[50:53]
	s_waitcnt lgkmcnt(0)
	v_mfma_f32_16x16x32_bf16 v[46:49], v[114:117], v[126:129], v[46:49]
	ds_read_b128 v[180:183], v112 offset:36864
	ds_read_b128 v[184:187], v112 offset:38912
	v_mfma_f32_16x16x32_bf16 v[42:45], v[118:121], v[126:129], v[42:45]
	v_mfma_f32_16x16x32_bf16 v[38:41], v[156:159], v[126:129], v[38:41]
	v_mfma_f32_16x16x32_bf16 v[34:37], v[160:163], v[126:129], v[34:37]
	s_waitcnt lgkmcnt(1)
	v_mfma_f32_16x16x32_bf16 v[30:33], v[114:117], v[180:183], v[30:33]
	ds_read_b128 v[164:167], v189 offset:49168
	ds_read_b128 v[168:171], v189 offset:49680
	v_mfma_f32_16x16x32_bf16 v[26:29], v[118:121], v[180:183], v[26:29]
	v_mfma_f32_16x16x32_bf16 v[22:25], v[156:159], v[180:183], v[22:25]
	ds_read_b128 v[172:175], v189 offset:53264
	ds_read_b128 v[176:179], v189 offset:53776
	v_mfma_f32_16x16x32_bf16 v[18:21], v[160:163], v[180:183], v[18:21]
	s_waitcnt lgkmcnt(4)
	v_mfma_f32_16x16x32_bf16 v[14:17], v[114:117], v[184:187], v[14:17]
	ds_read_b128 v[122:125], v113 offset:32768
	ds_read_b128 v[126:129], v113 offset:34816
	v_mfma_f32_16x16x32_bf16 v[10:13], v[118:121], v[184:187], v[10:13]
	v_mfma_f32_16x16x32_bf16 v[6:9], v[156:159], v[184:187], v[6:9]
	v_mfma_f32_16x16x32_bf16 v[2:5], v[160:163], v[184:187], v[2:5]
	s_waitcnt lgkmcnt(1)
	v_mfma_f32_16x16x32_bf16 v[66:69], v[164:167], v[122:125], v[66:69]
	v_mfma_f32_16x16x32_bf16 v[58:61], v[168:171], v[122:125], v[58:61]
	v_mfma_f32_16x16x32_bf16 v[54:57], v[172:175], v[122:125], v[54:57]
	v_mfma_f32_16x16x32_bf16 v[50:53], v[176:179], v[122:125], v[50:53]
	s_waitcnt lgkmcnt(0)
	v_mfma_f32_16x16x32_bf16 v[46:49], v[164:167], v[126:129], v[46:49]
	ds_read_b128 v[180:183], v113 offset:36864
	ds_read_b128 v[184:187], v113 offset:38912
	v_mfma_f32_16x16x32_bf16 v[42:45], v[168:171], v[126:129], v[42:45]
	v_mfma_f32_16x16x32_bf16 v[38:41], v[172:175], v[126:129], v[38:41]
	v_mfma_f32_16x16x32_bf16 v[34:37], v[176:179], v[126:129], v[34:37]
	s_waitcnt lgkmcnt(1)
	v_mfma_f32_16x16x32_bf16 v[30:33], v[164:167], v[180:183], v[30:33]
	v_mfma_f32_16x16x32_bf16 v[26:29], v[168:171], v[180:183], v[26:29]
	v_mfma_f32_16x16x32_bf16 v[22:25], v[172:175], v[180:183], v[22:25]
	v_mfma_f32_16x16x32_bf16 v[18:21], v[176:179], v[180:183], v[18:21]
	s_waitcnt lgkmcnt(0)
	v_mfma_f32_16x16x32_bf16 v[14:17], v[164:167], v[184:187], v[14:17]
	v_mfma_f32_16x16x32_bf16 v[10:13], v[168:171], v[184:187], v[10:13]
	v_mfma_f32_16x16x32_bf16 v[6:9], v[172:175], v[184:187], v[6:9]
	v_mfma_f32_16x16x32_bf16 v[2:5], v[176:179], v[184:187], v[2:5]
	s_barrier

.Lgq_o:
	ds_read_b128 v[114:117], v188 offset:16384
	ds_read_b128 v[122:125], v188 offset:16896
	ds_read_b128 v[126:129], v188 offset:20480
	ds_read_b128 v[156:159], v188 offset:20992
	ds_read_b128 v[118:121], v112
	ds_read_b128 v[160:163], v112 offset:2048
	s_waitcnt lgkmcnt(1)
	v_mfma_f32_16x16x32_bf16 v[94:97], v[114:117], v[118:121], v[94:97]
	s_waitcnt vmcnt(7)
	ds_write_b128 v108, v[224:227] offset:32768
	v_mfma_f32_16x16x32_bf16 v[90:93], v[122:125], v[118:121], v[90:93]
	global_load_dwordx4 v[2:5], v216, s[10:11] offset:256
	v_mfma_f32_16x16x32_bf16 v[86:89], v[126:129], v[118:121], v[86:89]
	v_mfma_f32_16x16x32_bf16 v[82:85], v[156:159], v[118:121], v[82:85]
	s_waitcnt vmcnt(7)
	ds_write_b128 v108, v[228:231] offset:36864
	s_waitcnt lgkmcnt(2)
	v_mfma_f32_16x16x32_bf16 v[78:81], v[114:117], v[160:163], v[78:81]
	ds_read_b128 v[180:183], v112 offset:4096
	ds_read_b128 v[184:187], v112 offset:6144
	v_mfma_f32_16x16x32_bf16 v[74:77], v[122:125], v[160:163], v[74:77]
	global_load_dwordx4 v[6:9], v217, s[10:11] offset:256
	v_mfma_f32_16x16x32_bf16 v[70:73], v[126:129], v[160:163], v[70:73]
	s_waitcnt vmcnt(7)
	ds_write_b128 v108, v[232:235] offset:40960
	v_mfma_f32_16x16x32_bf16 v[66:69], v[156:159], v[160:163], v[66:69]
	s_waitcnt lgkmcnt(2)
	v_mfma_f32_16x16x32_bf16 v[62:65], v[114:117], v[180:183], v[62:65]
	ds_read_b128 v[164:167], v189 offset:16384
	ds_read_b128 v[168:171], v189 offset:16896
	v_mfma_f32_16x16x32_bf16 v[58:61], v[122:125], v[180:183], v[58:61]
	s_waitcnt vmcnt(6)
	ds_write_b128 v108, v[236:239] offset:45056
	v_mfma_f32_16x16x32_bf16 v[54:57], v[126:129], v[180:183], v[54:57]
	ds_read_b128 v[172:175], v189 offset:20480
	ds_read_b128 v[176:179], v189 offset:20992
	v_mfma_f32_16x16x32_bf16 v[50:53], v[156:159], v[180:183], v[50:53]
	global_load_dwordx4 v[10:13], v218, s[10:11] offset:256
	s_waitcnt lgkmcnt(6)
	v_mfma_f32_16x16x32_bf16 v[46:49], v[114:117], v[184:187], v[46:49]
	ds_read_b128 v[118:121], v113
	ds_read_b128 v[160:163], v113 offset:2048
	v_mfma_f32_16x16x32_bf16 v[42:45], v[122:125], v[184:187], v[42:45]
	s_waitcnt vmcnt(6)
	ds_write_b128 v190, v[240:243] offset:49168
	v_mfma_f32_16x16x32_bf16 v[38:41], v[126:129], v[184:187], v[38:41]
	global_load_dwordx4 v[14:17], v219, s[10:11] offset:256
	v_mfma_f32_16x16x32_bf16 v[34:37], v[156:159], v[184:187], v[34:37]
	s_waitcnt lgkmcnt(2)
	v_mfma_f32_16x16x32_bf16 v[94:97], v[164:167], v[118:121], v[94:97]
	s_waitcnt vmcnt(6)
	ds_write_b128 v190, v[244:247] offset:53264
	v_mfma_f32_16x16x32_bf16 v[90:93], v[168:171], v[118:121], v[90:93]
	global_load_dwordx4 v[18:21], v216, s[28:29] offset:256
	v_mfma_f32_16x16x32_bf16 v[86:89], v[172:175], v[118:121], v[86:89]
	v_mfma_f32_16x16x32_bf16 v[82:85], v[176:179], v[118:121], v[82:85]
	s_waitcnt vmcnt(6)
	ds_write_b128 v190, v[248:251] offset:57360
	s_waitcnt lgkmcnt(3)
	v_mfma_f32_16x16x32_bf16 v[78:81], v[164:167], v[160:163], v[78:81]
	ds_read_b128 v[180:183], v113 offset:4096
	ds_read_b128 v[184:187], v113 offset:6144
	v_mfma_f32_16x16x32_bf16 v[74:77], v[168:171], v[160:163], v[74:77]
	global_load_dwordx4 v[22:25], v217, s[28:29] offset:256
	v_mfma_f32_16x16x32_bf16 v[70:73], v[172:175], v[160:163], v[70:73]
	s_waitcnt vmcnt(6)
	ds_write_b128 v190, v[252:255] offset:61456
	v_mfma_f32_16x16x32_bf16 v[66:69], v[176:179], v[160:163], v[66:69]
	s_waitcnt lgkmcnt(2)
	v_mfma_f32_16x16x32_bf16 v[62:65], v[164:167], v[180:183], v[62:65]
	global_load_dwordx4 v[26:29], v218, s[28:29] offset:256
	v_mfma_f32_16x16x32_bf16 v[58:61], v[168:171], v[180:183], v[58:61]
	v_mfma_f32_16x16x32_bf16 v[54:57], v[172:175], v[180:183], v[54:57]
	v_mfma_f32_16x16x32_bf16 v[50:53], v[176:179], v[180:183], v[50:53]
	global_load_dwordx4 v[30:33], v219, s[28:29] offset:256
	s_waitcnt lgkmcnt(1)
	v_mfma_f32_16x16x32_bf16 v[46:49], v[164:167], v[184:187], v[46:49]
	v_mfma_f32_16x16x32_bf16 v[42:45], v[168:171], v[184:187], v[42:45]
	v_mfma_f32_16x16x32_bf16 v[38:41], v[172:175], v[184:187], v[38:41]
	v_mfma_f32_16x16x32_bf16 v[34:37], v[176:179], v[184:187], v[34:37]
	s_waitcnt lgkmcnt(0)
	s_barrier
	s_add_u32 s10, s10, 0x80
	s_addc_u32 s11, s11, 0
	s_add_u32 s28, s28, 0x80
	s_addc_u32 s29, s29, 0
	ds_read_b128 v[114:117], v188 offset:49168
	ds_read_b128 v[122:125], v188 offset:49680
	ds_read_b128 v[126:129], v188 offset:53264
	ds_read_b128 v[156:159], v188 offset:53776
	ds_read_b128 v[118:121], v112 offset:32768
	ds_read_b128 v[160:163], v112 offset:34816
	s_waitcnt lgkmcnt(1)
	v_mfma_f32_16x16x32_bf16 v[94:97], v[114:117], v[118:121], v[94:97]
	s_waitcnt vmcnt(7)
	ds_write_b128 v108, v[2:5]
	v_mfma_f32_16x16x32_bf16 v[90:93], v[122:125], v[118:121], v[90:93]
	global_load_dwordx4 v[224:227], v216, s[10:11] offset:256
	v_mfma_f32_16x16x32_bf16 v[86:89], v[126:129], v[118:121], v[86:89]
	v_mfma_f32_16x16x32_bf16 v[82:85], v[156:159], v[118:121], v[82:85]
	s_waitcnt vmcnt(7)
	ds_write_b128 v108, v[6:9] offset:4096
	s_waitcnt lgkmcnt(2)
	v_mfma_f32_16x16x32_bf16 v[78:81], v[114:117], v[160:163], v[78:81]
	ds_read_b128 v[180:183], v112 offset:36864
	ds_read_b128 v[184:187], v112 offset:38912
	v_mfma_f32_16x16x32_bf16 v[74:77], v[122:125], v[160:163], v[74:77]
	global_load_dwordx4 v[228:231], v217, s[10:11] offset:256
	v_mfma_f32_16x16x32_bf16 v[70:73], v[126:129], v[160:163], v[70:73]
	s_waitcnt vmcnt(7)
	ds_write_b128 v108, v[10:13] offset:8192
	v_mfma_f32_16x16x32_bf16 v[66:69], v[156:159], v[160:163], v[66:69]
	s_waitcnt lgkmcnt(2)
	v_mfma_f32_16x16x32_bf16 v[62:65], v[114:117], v[180:183], v[62:65]
	ds_read_b128 v[164:167], v189 offset:49168
	ds_read_b128 v[168:171], v189 offset:49680
	v_mfma_f32_16x16x32_bf16 v[58:61], v[122:125], v[180:183], v[58:61]
	s_waitcnt vmcnt(6)
	ds_write_b128 v108, v[14:17] offset:12288
	v_mfma_f32_16x16x32_bf16 v[54:57], v[126:129], v[180:183], v[54:57]
	ds_read_b128 v[172:175], v189 offset:53264
	ds_read_b128 v[176:179], v189 offset:53776
	v_mfma_f32_16x16x32_bf16 v[50:53], v[156:159], v[180:183], v[50:53]
	global_load_dwordx4 v[232:235], v218, s[10:11] offset:256
	s_waitcnt lgkmcnt(6)
	v_mfma_f32_16x16x32_bf16 v[46:49], v[114:117], v[184:187], v[46:49]
	ds_read_b128 v[118:121], v113 offset:32768
	ds_read_b128 v[160:163], v113 offset:34816
	v_mfma_f32_16x16x32_bf16 v[42:45], v[122:125], v[184:187], v[42:45]
	s_waitcnt vmcnt(6)
	ds_write_b128 v190, v[18:21] offset:16384
	v_mfma_f32_16x16x32_bf16 v[38:41], v[126:129], v[184:187], v[38:41]
	global_load_dwordx4 v[236:239], v219, s[10:11] offset:256
	v_mfma_f32_16x16x32_bf16 v[34:37], v[156:159], v[184:187], v[34:37]
	s_waitcnt lgkmcnt(2)
	v_mfma_f32_16x16x32_bf16 v[94:97], v[164:167], v[118:121], v[94:97]
	s_waitcnt vmcnt(6)
	ds_write_b128 v190, v[22:25] offset:20480
	v_mfma_f32_16x16x32_bf16 v[90:93], v[168:171], v[118:121], v[90:93]
	global_load_dwordx4 v[240:243], v216, s[28:29] offset:256
	v_mfma_f32_16x16x32_bf16 v[86:89], v[172:175], v[118:121], v[86:89]
	v_mfma_f32_16x16x32_bf16 v[82:85], v[176:179], v[118:121], v[82:85]
	s_waitcnt vmcnt(6)
	ds_write_b128 v190, v[26:29] offset:24576
	s_waitcnt lgkmcnt(3)
	v_mfma_f32_16x16x32_bf16 v[78:81], v[164:167], v[160:163], v[78:81]
	ds_read_b128 v[180:183], v113 offset:36864
	ds_read_b128 v[184:187], v113 offset:38912
	v_mfma_f32_16x16x32_bf16 v[74:77], v[168:171], v[160:163], v[74:77]
	global_load_dwordx4 v[244:247], v217, s[28:29] offset:256
	v_mfma_f32_16x16x32_bf16 v[70:73], v[172:175], v[160:163], v[70:73]
	s_waitcnt vmcnt(6)
	ds_write_b128 v190, v[30:33] offset:28672
	v_mfma_f32_16x16x32_bf16 v[66:69], v[176:179], v[160:163], v[66:69]
	s_waitcnt lgkmcnt(2)
	v_mfma_f32_16x16x32_bf16 v[62:65], v[164:167], v[180:183], v[62:65]
	global_load_dwordx4 v[248:251], v218, s[28:29] offset:256
	v_mfma_f32_16x16x32_bf16 v[58:61], v[168:171], v[180:183], v[58:61]
	v_mfma_f32_16x16x32_bf16 v[54:57], v[172:175], v[180:183], v[54:57]
	v_mfma_f32_16x16x32_bf16 v[50:53], v[176:179], v[180:183], v[50:53]
	global_load_dwordx4 v[252:255], v219, s[28:29] offset:256
	s_waitcnt lgkmcnt(1)
	v_mfma_f32_16x16x32_bf16 v[46:49], v[164:167], v[184:187], v[46:49]
	v_mfma_f32_16x16x32_bf16 v[42:45], v[168:171], v[184:187], v[42:45]
	v_mfma_f32_16x16x32_bf16 v[38:41], v[172:175], v[184:187], v[38:41]
	v_mfma_f32_16x16x32_bf16 v[34:37], v[176:179], v[184:187], v[34:37]
	s_waitcnt lgkmcnt(0)
	s_barrier
	s_add_u32 s10, s10, 0x80
	s_addc_u32 s11, s11, 0
	s_add_u32 s28, s28, 0x80
	s_addc_u32 s29, s29, 0
	s_sub_i32 vcc_lo, vcc_lo, 1
	s_cmp_lg_u32 vcc_lo, 0
	s_cbranch_scc1 .Lgq_o
	ds_read_b128 v[114:117], v188 offset:16384
	ds_read_b128 v[122:125], v188 offset:16896
	ds_read_b128 v[126:129], v188 offset:20480
	ds_read_b128 v[156:159], v188 offset:20992
	ds_read_b128 v[118:121], v112
	ds_read_b128 v[160:163], v112 offset:2048
	s_waitcnt lgkmcnt(1)
	v_mfma_f32_16x16x32_bf16 v[94:97], v[114:117], v[118:121], v[94:97]
	s_waitcnt vmcnt(7)
	ds_write_b128 v108, v[224:227] offset:32768
	v_mfma_f32_16x16x32_bf16 v[90:93], v[122:125], v[118:121], v[90:93]
	v_mfma_f32_16x16x32_bf16 v[86:89], v[126:129], v[118:121], v[86:89]
	v_mfma_f32_16x16x32_bf16 v[82:85], v[156:159], v[118:121], v[82:85]
	s_waitcnt vmcnt(6)
	ds_write_b128 v108, v[228:231] offset:36864
	s_waitcnt lgkmcnt(2)
	v_mfma_f32_16x16x32_bf16 v[78:81], v[114:117], v[160:163], v[78:81]
	ds_read_b128 v[180:183], v112 offset:4096
	ds_read_b128 v[184:187], v112 offset:6144
	v_mfma_f32_16x16x32_bf16 v[74:77], v[122:125], v[160:163], v[74:77]
	v_mfma_f32_16x16x32_bf16 v[70:73], v[126:129], v[160:163], v[70:73]
	s_waitcnt vmcnt(5)
	ds_write_b128 v108, v[232:235] offset:40960
	v_mfma_f32_16x16x32_bf16 v[66:69], v[156:159], v[160:163], v[66:69]
	s_waitcnt lgkmcnt(2)
	v_mfma_f32_16x16x32_bf16 v[62:65], v[114:117], v[180:183], v[62:65]
	ds_read_b128 v[164:167], v189 offset:16384
	ds_read_b128 v[168:171], v189 offset:16896
	v_mfma_f32_16x16x32_bf16 v[58:61], v[122:125], v[180:183], v[58:61]
	s_waitcnt vmcnt(4)
	ds_write_b128 v108, v[236:239] offset:45056
	v_mfma_f32_16x16x32_bf16 v[54:57], v[126:129], v[180:183], v[54:57]
	ds_read_b128 v[172:175], v189 offset:20480
	ds_read_b128 v[176:179], v189 offset:20992
	v_mfma_f32_16x16x32_bf16 v[50:53], v[156:159], v[180:183], v[50:53]
	s_waitcnt lgkmcnt(6)
	v_mfma_f32_16x16x32_bf16 v[46:49], v[114:117], v[184:187], v[46:49]
	ds_read_b128 v[118:121], v113
	ds_read_b128 v[160:163], v113 offset:2048
	v_mfma_f32_16x16x32_bf16 v[42:45], v[122:125], v[184:187], v[42:45]
	s_waitcnt vmcnt(3)
	ds_write_b128 v190, v[240:243] offset:49168
	v_mfma_f32_16x16x32_bf16 v[38:41], v[126:129], v[184:187], v[38:41]
	v_mfma_f32_16x16x32_bf16 v[34:37], v[156:159], v[184:187], v[34:37]
	s_waitcnt lgkmcnt(2)
	v_mfma_f32_16x16x32_bf16 v[94:97], v[164:167], v[118:121], v[94:97]
	s_waitcnt vmcnt(2)
	ds_write_b128 v190, v[244:247] offset:53264
	v_mfma_f32_16x16x32_bf16 v[90:93], v[168:171], v[118:121], v[90:93]
	v_mfma_f32_16x16x32_bf16 v[86:89], v[172:175], v[118:121], v[86:89]
	v_mfma_f32_16x16x32_bf16 v[82:85], v[176:179], v[118:121], v[82:85]
	s_waitcnt vmcnt(1)
	ds_write_b128 v190, v[248:251] offset:57360
	s_waitcnt lgkmcnt(3)
	v_mfma_f32_16x16x32_bf16 v[78:81], v[164:167], v[160:163], v[78:81]
	ds_read_b128 v[180:183], v113 offset:4096
	ds_read_b128 v[184:187], v113 offset:6144
	v_mfma_f32_16x16x32_bf16 v[74:77], v[168:171], v[160:163], v[74:77]
	v_mfma_f32_16x16x32_bf16 v[70:73], v[172:175], v[160:163], v[70:73]
	s_waitcnt vmcnt(0)
	ds_write_b128 v190, v[252:255] offset:61456
	v_mfma_f32_16x16x32_bf16 v[66:69], v[176:179], v[160:163], v[66:69]
	s_waitcnt lgkmcnt(2)
	v_mfma_f32_16x16x32_bf16 v[62:65], v[164:167], v[180:183], v[62:65]
	v_mfma_f32_16x16x32_bf16 v[58:61], v[168:171], v[180:183], v[58:61]
	v_mfma_f32_16x16x32_bf16 v[54:57], v[172:175], v[180:183], v[54:57]
	v_mfma_f32_16x16x32_bf16 v[50:53], v[176:179], v[180:183], v[50:53]
	s_waitcnt lgkmcnt(1)
	v_mfma_f32_16x16x32_bf16 v[46:49], v[164:167], v[184:187], v[46:49]
	v_mfma_f32_16x16x32_bf16 v[42:45], v[168:171], v[184:187], v[42:45]
	v_mfma_f32_16x16x32_bf16 v[38:41], v[172:175], v[184:187], v[38:41]
	v_mfma_f32_16x16x32_bf16 v[34:37], v[176:179], v[184:187], v[34:37]
	s_waitcnt lgkmcnt(0)
	s_barrier
	ds_read_b128 v[114:117], v188 offset:49168
	ds_read_b128 v[122:125], v188 offset:49680
	ds_read_b128 v[126:129], v188 offset:53264
	ds_read_b128 v[156:159], v188 offset:53776
	ds_read_b128 v[118:121], v112 offset:32768
	ds_read_b128 v[160:163], v112 offset:34816
	s_waitcnt lgkmcnt(1)
	v_mfma_f32_16x16x32_bf16 v[94:97], v[114:117], v[118:121], v[94:97]
	v_mfma_f32_16x16x32_bf16 v[90:93], v[122:125], v[118:121], v[90:93]
	v_mfma_f32_16x16x32_bf16 v[86:89], v[126:129], v[118:121], v[86:89]
	v_mfma_f32_16x16x32_bf16 v[82:85], v[156:159], v[118:121], v[82:85]
	s_waitcnt lgkmcnt(0)
	v_mfma_f32_16x16x32_bf16 v[78:81], v[114:117], v[160:163], v[78:81]
	ds_read_b128 v[180:183], v112 offset:36864
	ds_read_b128 v[184:187], v112 offset:38912
	v_mfma_f32_16x16x32_bf16 v[74:77], v[122:125], v[160:163], v[74:77]
	v_mfma_f32_16x16x32_bf16 v[70:73], v[126:129], v[160:163], v[70:73]
	v_mfma_f32_16x16x32_bf16 v[66:69], v[156:159], v[160:163], v[66:69]
	s_waitcnt lgkmcnt(1)
	v_mfma_f32_16x16x32_bf16 v[62:65], v[114:117], v[180:183], v[62:65]
	ds_read_b128 v[164:167], v189 offset:49168
	ds_read_b128 v[168:171], v189 offset:49680
	v_mfma_f32_16x16x32_bf16 v[58:61], v[122:125], v[180:183], v[58:61]
	v_mfma_f32_16x16x32_bf16 v[54:57], v[126:129], v[180:183], v[54:57]
	ds_read_b128 v[172:175], v189 offset:53264
	ds_read_b128 v[176:179], v189 offset:53776
	v_mfma_f32_16x16x32_bf16 v[50:53], v[156:159], v[180:183], v[50:53]
	s_waitcnt lgkmcnt(4)
	v_mfma_f32_16x16x32_bf16 v[46:49], v[114:117], v[184:187], v[46:49]
	ds_read_b128 v[118:121], v113 offset:32768
	ds_read_b128 v[160:163], v113 offset:34816
	v_mfma_f32_16x16x32_bf16 v[42:45], v[122:125], v[184:187], v[42:45]
	v_mfma_f32_16x16x32_bf16 v[38:41], v[126:129], v[184:187], v[38:41]
	v_mfma_f32_16x16x32_bf16 v[34:37], v[156:159], v[184:187], v[34:37]
	s_waitcnt lgkmcnt(1)
	v_mfma_f32_16x16x32_bf16 v[94:97], v[164:167], v[118:121], v[94:97]
	v_mfma_f32_16x16x32_bf16 v[90:93], v[168:171], v[118:121], v[90:93]
	v_mfma_f32_16x16x32_bf16 v[86:89], v[172:175], v[118:121], v[86:89]
	v_mfma_f32_16x16x32_bf16 v[82:85], v[176:179], v[118:121], v[82:85]
	s_waitcnt lgkmcnt(0)
	v_mfma_f32_16x16x32_bf16 v[78:81], v[164:167], v[160:163], v[78:81]
	ds_read_b128 v[180:183], v113 offset:36864
	ds_read_b128 v[184:187], v113 offset:38912
	v_mfma_f32_16x16x32_bf16 v[74:77], v[168:171], v[160:163], v[74:77]
	v_mfma_f32_16x16x32_bf16 v[70:73], v[172:175], v[160:163], v[70:73]
	v_mfma_f32_16x16x32_bf16 v[66:69], v[176:179], v[160:163], v[66:69]
	s_waitcnt lgkmcnt(1)
	v_mfma_f32_16x16x32_bf16 v[62:65], v[164:167], v[180:183], v[62:65]
	v_mfma_f32_16x16x32_bf16 v[58:61], v[168:171], v[180:183], v[58:61]
	v_mfma_f32_16x16x32_bf16 v[54:57], v[172:175], v[180:183], v[54:57]
	v_mfma_f32_16x16x32_bf16 v[50:53], v[176:179], v[180:183], v[50:53]
	s_waitcnt lgkmcnt(0)
	v_mfma_f32_16x16x32_bf16 v[46:49], v[164:167], v[184:187], v[46:49]
	v_mfma_f32_16x16x32_bf16 v[42:45], v[168:171], v[184:187], v[42:45]
	v_mfma_f32_16x16x32_bf16 v[38:41], v[172:175], v[184:187], v[38:41]
	v_mfma_f32_16x16x32_bf16 v[34:37], v[176:179], v[184:187], v[34:37]
	s_barrier
	s_branch .LBB0_1383
